# layer-0 P4/P5 item loops: last 2 hyena rounds of CUs<128 (which carry an extra GEMM unit + attention item) moved to CUs>=128
# baseline (speedup 1.0000x reference)
.LBB0_611:
	v_readlane_b32 s0, v255, 14
	v_readlane_b32 s1, v255, 15
	s_and_b64 s[0:1], s[0:1], exec
	s_movk_i32 s0, 0x500
	s_cselect_b32 s74, s0, 0x400
	s_movk_i32 s0, 0x400
	s_cselect_b32 s64, 0x480, s0
	s_or_b32 s5, s64, 0x100
	s_add_i32 s22, s5, s74
	s_cmpk_eq_u32 s74, 0x500
	s_cselect_b32 s0, 0x200, 0
	s_cmpk_lt_u32 s54, 0x80
	s_cselect_b32 s0, s0, 0
	s_sub_i32 s22, s22, s0
	s_cmp_ge_i32 s54, s22
	s_mul_i32 s16, s6, 0x900
	s_mul_i32 s14, s6, 0x300
	s_cbranch_scc1 .LBB0_790
	v_readlane_b32 s0, v255, 14
	v_readlane_b32 s76, v252, 0
	v_readlane_b32 s1, v255, 15
	v_readlane_b32 s77, v252, 1
	v_readlane_b32 s78, v252, 2
	v_readlane_b32 s79, v252, 3
	v_readlane_b32 s80, v252, 4
	v_readlane_b32 s81, v252, 5
	v_readlane_b32 s82, v252, 6
	v_readlane_b32 s83, v252, 7
	v_readlane_b32 s84, v252, 8
	v_readlane_b32 s85, v252, 9
	v_readlane_b32 s86, v252, 10
	v_readlane_b32 s87, v252, 11
	v_readlane_b32 s88, v252, 12
	v_readlane_b32 s89, v252, 13
	v_readlane_b32 s90, v252, 14
	v_readlane_b32 s91, v252, 15
	s_and_b64 s[0:1], s[0:1], exec
	s_mov_b32 s13, s77
	s_mov_b32 s17, s77
	v_readlane_b32 s76, v252, 44
	s_movk_i32 s0, 0xfa80
	v_readlane_b32 s78, v252, 46
	v_readlane_b32 s79, v252, 47
	s_cselect_b32 s23, s0, 0xfffffb00
	s_lshl_b64 s[0:1], s[16:17], 2
	s_mov_b64 s[6:7], s[78:79]
	v_readlane_b32 s80, v252, 48
	v_readlane_b32 s81, v252, 49
	s_add_u32 s17, s6, s0
	s_mov_b32 s15, s13
	s_mov_b64 s[8:9], s[80:81]
	s_addc_u32 s28, s7, s1
	s_lshl_b64 s[0:1], s[14:15], 2
	v_readlane_b32 s90, v252, 58
	v_readlane_b32 s91, v252, 59
	s_add_u32 s15, s8, s0
	v_readlane_b32 s6, v255, 10
	v_readlane_b32 s90, v254, 49
	v_readlane_b32 s80, v254, 55
	v_readlane_b32 s78, v254, 53
	s_addc_u32 s29, s9, s1
	s_lshl_b32 s0, s6, 10
	v_readlane_b32 s91, v254, 50
	v_readlane_b32 s81, v254, 56
	v_readlane_b32 s79, v254, 54
	s_lshl_b32 s34, s6, 9
	s_or_b32 s52, s0, 0x200
	s_lshl_b32 s75, s6, 3
	s_mov_b32 s35, s54
	v_readlane_b32 s77, v252, 45
	v_readlane_b32 s82, v252, 50
	v_readlane_b32 s83, v252, 51
	v_readlane_b32 s84, v252, 52
	v_readlane_b32 s85, v252, 53
	v_readlane_b32 s86, v252, 54
	v_readlane_b32 s87, v252, 55
	v_readlane_b32 s88, v252, 56
	v_readlane_b32 s89, v252, 57
	v_readlane_b32 s7, v255, 11
	s_branch .LBB0_615

.LBB0_614:
	v_readlane_b32 s36, v252, 18
	v_readlane_b32 s42, v252, 24
	v_readlane_b32 s37, v252, 19
	v_readlane_b32 s38, v252, 20
	v_readlane_b32 s39, v252, 21
	v_readlane_b32 s40, v252, 22
	v_readlane_b32 s41, v252, 23
	v_readlane_b32 s43, v252, 25
	v_readlane_b32 s0, v255, 14
	v_readlane_b32 s1, v255, 15
	s_or_b32 s0, s0, s1
	s_cmp_lg_u32 s0, 0
	s_cselect_b32 s0, s54, 0
	s_and_b32 s0, s0, 0x80
	s_cbranch_scc0 .Lrb4_nat
	s_bitcmp1_b32 s35, 7
	s_cbranch_scc0 .Lrb4_ext
	s_add_i32 s35, s35, s42
	s_cmp_ge_i32 s35, s22
	s_cbranch_scc0 .LBB0_615
	s_sub_i32 s35, s35, 0x80
	s_branch .LBB0_615
.Lrb4_ext:
	s_sub_i32 s35, s35, s42
	s_cmpk_lt_i32 s35, 0x880
	s_cbranch_scc1 .LBB0_790
	s_branch .LBB0_615
.Lrb4_nat:
	s_add_i32 s35, s35, s42
	s_cmp_ge_i32 s35, s22
	s_cbranch_scc1 .LBB0_790

.LBB0_842:
	s_or_b64 exec, exec, s[0:1]
	s_lshl_b32 s25, s64, 1
	s_add_i32 s20, s25, s74
	s_cmpk_eq_u32 s74, 0x500
	s_cselect_b32 s0, 0x200, 0
	s_cmpk_lt_u32 s54, 0x80
	s_cselect_b32 s0, s0, 0
	s_sub_i32 s20, s20, s0
	v_readlane_b32 s74, v254, 59
	s_cmp_ge_i32 s54, s20
	v_readlane_b32 s75, v254, 60
	s_waitcnt lgkmcnt(0)
	s_barrier
	s_cbranch_scc1 .LBB0_954
	v_readlane_b32 s76, v252, 0
	v_readlane_b32 s77, v252, 1
	v_readlane_b32 s78, v252, 2
	v_readlane_b32 s79, v252, 3
	v_readlane_b32 s80, v252, 4
	v_readlane_b32 s81, v252, 5
	v_readlane_b32 s82, v252, 6
	v_readlane_b32 s83, v252, 7
	v_readlane_b32 s84, v252, 8
	v_readlane_b32 s85, v252, 9
	v_readlane_b32 s86, v252, 10
	v_readlane_b32 s87, v252, 11
	v_readlane_b32 s88, v252, 12
	v_readlane_b32 s89, v252, 13
	v_readlane_b32 s90, v252, 14
	v_readlane_b32 s91, v252, 15
	s_mov_b32 s5, s77
	s_mov_b32 s17, s77
	v_readlane_b32 s76, v252, 44
	v_readlane_b32 s78, v252, 46
	v_readlane_b32 s79, v252, 47
	s_lshl_b64 s[0:1], s[16:17], 2
	s_mov_b64 s[6:7], s[78:79]
	v_readlane_b32 s80, v252, 48
	v_readlane_b32 s81, v252, 49
	s_add_u32 s21, s6, s0
	s_mov_b32 s15, s5
	s_mov_b64 s[8:9], s[80:81]
	s_addc_u32 s22, s7, s1
	s_lshl_b64 s[0:1], s[14:15], 2
	s_add_u32 s23, s8, s0
	v_readlane_b32 s88, v252, 56
	s_addc_u32 s28, s9, s1
	v_readlane_b32 s0, v255, 10
	v_readlane_b32 s84, v252, 52
	v_readlane_b32 s85, v252, 53
	v_readlane_b32 s86, v252, 54
	v_readlane_b32 s87, v252, 55
	v_readlane_b32 s89, v252, 57
	v_readlane_b32 s90, v252, 58
	v_readlane_b32 s91, v252, 59
	v_readlane_b32 s80, v254, 55
	v_readlane_b32 s78, v254, 53
	s_lshl_b32 s29, s0, 9
	s_lshl_b32 s88, s0, 10
	s_mov_b32 s91, 0xd000
	s_movk_i32 s87, 0x5000
	s_mov_b32 s86, 0x30000
	s_mov_b32 s85, 0x9000
	s_mov_b32 s84, 0xc000
	s_movk_i32 s65, 0x4000
	s_mov_b32 s52, 0x20000
	v_readlane_b32 s81, v254, 56
	v_readlane_b32 s79, v254, 54
	s_or_b32 s34, s29, 0x100
	s_or_b32 s35, s88, 0x300
	s_bitset1_b32 s88, 8
	s_lshl_b32 s89, s0, 3
	s_mov_b32 s90, s54
	v_readlane_b32 s77, v252, 45
	v_readlane_b32 s82, v252, 50
	v_readlane_b32 s83, v252, 51
	v_readlane_b32 s1, v255, 11
	s_branch .LBB0_847

.LBB0_845:
.LBB0_846:
	v_readlane_b32 s4, v252, 18
	v_readlane_b32 s10, v252, 24
	v_readlane_b32 s5, v252, 19
	v_readlane_b32 s6, v252, 20
	v_readlane_b32 s7, v252, 21
	v_readlane_b32 s8, v252, 22
	v_readlane_b32 s9, v252, 23
	v_readlane_b32 s11, v252, 25
	v_readlane_b32 s0, v255, 14
	v_readlane_b32 s1, v255, 15
	s_or_b32 s0, s0, s1
	s_cmp_lg_u32 s0, 0
	s_cselect_b32 s0, s54, 0
	s_and_b32 s0, s0, 0x80
	s_cbranch_scc0 .Lrb5_nat
	s_bitcmp1_b32 s90, 7
	s_cbranch_scc0 .Lrb5_ext
	s_add_i32 s90, s90, s10
	s_cmp_ge_i32 s90, s20
	s_cbranch_scc0 .LBB0_847
	s_sub_i32 s90, s90, 0x180
	s_branch .LBB0_847
.Lrb5_ext:
	s_sub_i32 s90, s90, s10
	s_cmpk_lt_i32 s90, 0xc00
	s_cbranch_scc1 .LBB0_954
	s_branch .LBB0_847
.Lrb5_nat:
	s_add_i32 s90, s90, s10
	s_cmp_ge_i32 s90, s20
	s_cbranch_scc1 .LBB0_954
